# v093 + in-projection unit mapping strength-reduced (next unit = same row panel, column tile + 4)
# baseline (speedup 1.0000x reference)
.LBB0_230:
	s_add_i32 s80, s80, 1
	s_mul_i32 s6, s80, s89
	s_mul_hi_u32 s12, s80, s8
	s_add_i32 s12, s12, s6
	s_mul_i32 s6, s80, s8
	s_add_u32 s72, s6, s54
	s_addc_u32 s73, s12, s55
	v_mov_b64_e32 v[4:5], 0x280
	v_cmp_lt_i64_e64 s[12:13], s[72:73], v[4:5]
	v_mov_b64_e32 v[4:5], 0x27f
	v_cmp_gt_i64_e32 vcc, s[72:73], v[4:5]
	s_cbranch_vccnz .LBB0_232
	s_mov_b32 s70, s16
	s_add_i32 s68, s14, 4
